# attention loop top: tile store right after the first K reads, next-tile global loads moved into QK MFMA gap 2 (temps renamed), fewer adds before the first MFMA
# speedup vs baseline: 1.0038x; 1.0009x over previous
; #define GLOAD(kt_, KR, VR) do { _Pragma("unroll") for (int i = 0; i < KCH; ++i) if (krow_[i] < 64) KR[i] = *(const u32x4*)(kbase + (size_t)((kt_) * 64 + krow_[i]) * HK * DQ + kcol_[i]); \
;     VR = *(const u32x4*)(vbase + (size_t)(kt_) * 4096 + vrow * 64 + vcol); } while (0)
; template <int DQ>
; DI void attn_dense_item(const u16* __restrict__ Q, int qh, const u16* __restrict__ Kp, int HK, int kh, const u16* __restrict__ Vt,
;                         int S, int s0, int qblk, u16* __restrict__ MER, int ocol, float* __restrict__ ssqo, int slot, unsigned char* smem) {
;     ...
;     if (kt + 4 < nkt) { GLOAD(kt + 4, krA, vrA); GLOAD(kt + 5, krB, vrB); }
.Lmla_B_st_end:
	v_add_f32_e32 v201, v74, v201
	v_add_f32_e32 v247, v75, v76
	v_add_f32_e32 v201, v77, v201
	v_add_f32_e32 v247, v78, v247
	s_waitcnt lgkmcnt(6)
	v_mfma_f32_32x32x16_bf16 v[50:65], v[226:229], v[114:117], v[34:49]
	ds_read_b128 v[226:229], v0 offset:6688
	v_add_f32_e32 v201, v79, v201
	v_add_f32_e32 v247, v80, v247
	v_add_f32_e32 v201, v81, v201
	v_add_f32_e32 v247, v82, v247
	v_add_f32_e32 v201, v83, v201
	v_add_f32_e32 v247, v84, v247
	s_waitcnt lgkmcnt(6)
	v_mfma_f32_32x32x16_bf16 v[50:65], v[230:233], v[118:121], v[50:65]
	ds_read_b128 v[230:233], v0 offset:6720
	v_add_f32_e32 v201, v85, v201
	v_add_f32_e32 v247, v86, v247
	v_add_f32_e32 v201, v87, v201
	v_add_f32_e32 v247, v88, v247
	v_add_f32_e32 v201, v89, v201
	v_add_f32_e32 v247, v90, v247
	s_waitcnt lgkmcnt(6)
	v_mfma_f32_32x32x16_bf16 v[50:65], v[234:237], v[122:125], v[50:65]
	ds_read_b128 v[234:237], v0 offset:6752
.Lmla_B_312:
	s_cmp_ge_u32 s14, s23
	s_cbranch_scc1 .Lmla_B_ls_end
	s_and_saveexec_b64 s[6:7], s[0:1]
	s_cbranch_execz .Lmla_B_315
	global_load_dwordx4 v[138:141], v[176:177], off

.Lmla_B_317:
	s_or_b64 exec, exec, s[6:7]
	global_load_dwordx4 v[154:157], v[174:175], off
	s_mov_b64 vcc, 0x12000
	v_lshl_add_u64 v[252:253], v[176:177], 0, vcc
	s_and_saveexec_b64 s[6:7], s[0:1]
	s_cbranch_execz .Lmla_B_319
	global_load_dwordx4 v[146:149], v[252:253], off
.Lmla_B_319:
	s_or_b64 exec, exec, s[6:7]
	v_lshl_add_u64 v[252:253], v[178:179], 0, vcc
	s_and_saveexec_b64 s[6:7], s[4:5]
	s_cbranch_execz .Lmla_B_298
	global_load_dwordx4 v[150:153], v[252:253], off
.Lmla_B_298:
	s_or_b64 exec, exec, s[6:7]
	s_mov_b64 vcc, 0x2000
	v_lshl_add_u64 v[252:253], v[174:175], 0, vcc
	global_load_dwordx4 v[158:161], v[252:253], off
.Lmla_B_ls_end:
	s_add_i32 s6, s14, -4
	s_and_b32 s6, s6, 2
	s_mul_i32 s7, s6, 0x2400
	v_add_f32_e32 v201, v91, v201
	v_add_f32_e32 v247, v92, v247
	v_add_f32_e32 v201, v93, v201
	v_add_f32_e32 v247, v94, v247
	v_add_f32_e32 v201, v95, v201
	v_add_f32_e32 v247, v96, v247
	s_waitcnt lgkmcnt(6)
	v_mfma_f32_32x32x16_bf16 v[50:65], v[238:241], v[126:129], v[50:65]
	ds_read_b128 v[238:241], v0 offset:6784
	v_add_f32_e32 v201, v97, v201
	v_add_f32_e32 v247, v98, v247
	v_add_f32_e32 v201, v99, v201
	v_add_f32_e32 v247, v100, v247
	v_add_f32_e32 v201, v101, v201
	v_add_f32_e32 v247, v102, v247
	s_waitcnt lgkmcnt(6)
	v_mfma_f32_32x32x16_bf16 v[50:65], v[242:245], v[130:133], v[50:65]
	ds_read_b128 v[242:245], v0 offset:6816
	v_add_f32_e32 v201, v103, v201
	v_add_f32_e32 v247, v104, v247
	v_add_f32_e32 v201, v105, v201
	v_add_f32_e32 v247, v106, v247
	v_add_f32_e32 v201, v107, v201
	v_add_f32_e32 v247, v108, v247
	s_waitcnt lgkmcnt(6)
	v_mfma_f32_32x32x16_bf16 v[50:65], v[162:165], v[134:137], v[50:65]
	ds_read_b128 v[162:165], v225
	v_add_f32_e32 v201, v109, v201
	v_add_f32_e32 v247, v110, v247
	v_add_f32_e32 v201, v111, v201
	v_add_f32_e32 v247, v112, v247
	v_add_f32_e32 v201, v113, v201
	v_add_f32_e32 v247, v246, v247
	s_waitcnt lgkmcnt(6)
	v_mfma_f32_32x32x16_bf16 v[66:81], v[166:169], v[114:117], v[34:49]
	ds_read_b128 v[166:169], v225 offset:32
	v_add_f32_e32 v201, v202, v201
	v_add_f32_e32 v247, v203, v247
	v_add_f32_e32 v201, v204, v201
	v_add_f32_e32 v247, v205, v247
	s_waitcnt lgkmcnt(6)
	v_mfma_f32_32x32x16_bf16 v[66:81], v[226:229], v[118:121], v[66:81]
	ds_read_b128 v[226:229], v225 offset:64
	v_add_f32_e32 v201, v206, v201
	v_add_f32_e32 v247, v207, v247
	v_add_f32_e32 v201, v208, v201
	v_add_f32_e32 v247, v209, v247
	s_waitcnt lgkmcnt(6)
	v_mfma_f32_32x32x16_bf16 v[66:81], v[230:233], v[122:125], v[66:81]
	ds_read_b128 v[230:233], v225 offset:96
	v_add_f32_e32 v201, v210, v201
	v_add_f32_e32 v247, v211, v247
	v_add_f32_e32 v201, v212, v201
	v_add_f32_e32 v247, v213, v247
	v_max3_f32 v0, v50, v51, v52
	v_max3_f32 v0, v0, v53, v54
	s_waitcnt lgkmcnt(6)
	v_mfma_f32_32x32x16_bf16 v[66:81], v[234:237], v[126:129], v[66:81]
	ds_read_b128 v[234:237], v225 offset:128
	v_add_f32_e32 v201, v214, v201
	v_add_f32_e32 v247, v215, v247
	v_add_f32_e32 v201, v216, v201
	v_add_f32_e32 v247, v217, v247
	v_max3_f32 v0, v0, v55, v56
	v_max3_f32 v0, v0, v57, v58
	s_waitcnt lgkmcnt(6)
	v_mfma_f32_32x32x16_bf16 v[66:81], v[238:241], v[130:133], v[66:81]
	ds_read_b128 v[238:241], v225 offset:160
	v_add_f32_e32 v201, v218, v201
	v_add_f32_e32 v247, v219, v247
	v_add_f32_e32 v201, v220, v201
	v_add_f32_e32 v247, v221, v247
	v_max3_f32 v0, v0, v59, v60
	v_max3_f32 v0, v0, v61, v62
	s_waitcnt lgkmcnt(6)
	v_mfma_f32_32x32x16_bf16 v[66:81], v[242:245], v[134:137], v[66:81]
	ds_read_b128 v[242:245], v225 offset:6656
	v_add_f32_e32 v201, v222, v201
	v_add_f32_e32 v247, v223, v247
	v_add_f32_e32 v201, v224, v201
	v_add_f32_e32 v201, v247, v201
	v_max3_f32 v0, v0, v63, v64
	v_max3_f32 v0, v0, v65, v65
	s_waitcnt lgkmcnt(6)
	v_mfma_f32_32x32x16_bf16 v[82:97], v[162:165], v[114:117], v[34:49]
	ds_read_b128 v[162:165], v225 offset:6688
	s_waitcnt lgkmcnt(6)
	v_mfma_f32_32x32x16_bf16 v[82:97], v[166:169], v[118:121], v[82:97]
	ds_read_b128 v[166:169], v225 offset:6720
	v_add3_u32 v247, v198, s7, v200
	s_waitcnt lgkmcnt(6)
	v_mfma_f32_32x32x16_bf16 v[82:97], v[226:229], v[122:125], v[82:97]
	ds_read_b128 v[226:229], v225 offset:6752
	v_max3_f32 v0, v0, v66, v67
	v_max3_f32 v0, v0, v68, v69
	s_waitcnt lgkmcnt(6)
	v_mfma_f32_32x32x16_bf16 v[82:97], v[230:233], v[126:129], v[82:97]
	ds_read_b128 v[230:233], v225 offset:6784
	v_max3_f32 v0, v0, v70, v71
	v_max3_f32 v0, v0, v72, v73
	s_waitcnt lgkmcnt(6)
	v_mfma_f32_32x32x16_bf16 v[82:97], v[234:237], v[130:133], v[82:97]
	ds_read_b128 v[234:237], v225 offset:6816
	v_max3_f32 v0, v0, v74, v75
	v_max3_f32 v0, v0, v76, v77
	s_waitcnt lgkmcnt(6)
	v_mfma_f32_32x32x16_bf16 v[82:97], v[238:241], v[134:137], v[82:97]
	ds_read_b128 v[238:241], v247 offset:53248
	v_max3_f32 v0, v0, v78, v79
	v_max3_f32 v0, v0, v80, v81
	s_waitcnt lgkmcnt(6)
	v_mfma_f32_32x32x16_bf16 v[98:113], v[242:245], v[114:117], v[34:49]
	ds_read_b128 v[242:245], v247 offset:57856
	s_waitcnt lgkmcnt(6)
	v_mfma_f32_32x32x16_bf16 v[98:113], v[162:165], v[118:121], v[98:113]
	s_waitcnt lgkmcnt(5)
	v_mfma_f32_32x32x16_bf16 v[98:113], v[166:169], v[122:125], v[98:113]
	s_waitcnt lgkmcnt(4)
	v_mfma_f32_32x32x16_bf16 v[98:113], v[226:229], v[126:129], v[98:113]
	ds_read_b128 v[226:229], v247 offset:53280
	s_waitcnt lgkmcnt(4)
	v_mfma_f32_32x32x16_bf16 v[98:113], v[230:233], v[130:133], v[98:113]
	ds_read_b128 v[230:233], v247 offset:57888
	s_waitcnt lgkmcnt(4)
	v_mfma_f32_32x32x16_bf16 v[98:113], v[234:237], v[134:137], v[98:113]
	ds_read_b128 v[234:237], v247 offset:53312
	v_max3_f32 v0, v0, v82, v83
	v_max3_f32 v0, v0, v84, v85
	v_max3_f32 v0, v0, v86, v87
	v_max3_f32 v0, v0, v88, v89
	v_max3_f32 v0, v0, v90, v91
	v_max3_f32 v0, v0, v92, v93
	v_max3_f32 v0, v0, v94, v95
	v_max3_f32 v0, v0, v96, v97
	s_nop 4
	v_max3_f32 v0, v0, v98, v99
	v_max3_f32 v0, v0, v100, v101
	v_max3_f32 v0, v0, v102, v103
	v_max3_f32 v0, v0, v104, v105
	v_max3_f32 v0, v0, v106, v107
	v_max3_f32 v0, v0, v108, v109
	v_max3_f32 v0, v0, v110, v111
	v_max3_f32 v0, v0, v112, v113
	v_mov_b32_e32 v162, v0
	s_nop 1
	v_permlane32_swap_b32_e32 v0, v162
	v_max_f32_e32 v0, v0, v162
	v_cmp_lt_f32_e32 vcc, s50, v0
	s_cbranch_vccz .LBB0_302
	v_max_f32_e32 v0, v0, v0
	v_max_f32_e32 v0, 0, v0
	v_exp_f32_e64 v162, -v0
	v_pk_add_f32 v[50:51], v[50:51], v[0:1] op_sel_hi:[1,0] neg_lo:[0,1] neg_hi:[0,1]
	v_pk_add_f32 v[66:67], v[66:67], v[0:1] op_sel_hi:[1,0] neg_lo:[0,1] neg_hi:[0,1]
	v_pk_add_f32 v[82:83], v[82:83], v[0:1] op_sel_hi:[1,0] neg_lo:[0,1] neg_hi:[0,1]
	v_mul_f32_e32 v201, v201, v162
	v_pk_mul_f32 v[16:17], v[16:17], v[162:163] op_sel_hi:[1,0]
	v_pk_mul_f32 v[14:15], v[14:15], v[162:163] op_sel_hi:[1,0]
	v_pk_mul_f32 v[12:13], v[12:13], v[162:163] op_sel_hi:[1,0]
	v_pk_mul_f32 v[10:11], v[10:11], v[162:163] op_sel_hi:[1,0]
	v_pk_mul_f32 v[8:9], v[8:9], v[162:163] op_sel_hi:[1,0]
	v_pk_mul_f32 v[6:7], v[6:7], v[162:163] op_sel_hi:[1,0]
	v_pk_mul_f32 v[4:5], v[4:5], v[162:163] op_sel_hi:[1,0]
	v_pk_mul_f32 v[2:3], v[2:3], v[162:163] op_sel_hi:[1,0]
	v_pk_mul_f32 v[32:33], v[32:33], v[162:163] op_sel_hi:[1,0]
	v_pk_mul_f32 v[30:31], v[30:31], v[162:163] op_sel_hi:[1,0]
	v_pk_mul_f32 v[28:29], v[28:29], v[162:163] op_sel_hi:[1,0]
	v_pk_mul_f32 v[26:27], v[26:27], v[162:163] op_sel_hi:[1,0]
	v_pk_mul_f32 v[24:25], v[24:25], v[162:163] op_sel_hi:[1,0]
	v_pk_mul_f32 v[22:23], v[22:23], v[162:163] op_sel_hi:[1,0]
	v_pk_mul_f32 v[20:21], v[20:21], v[162:163] op_sel_hi:[1,0]
	v_pk_mul_f32 v[18:19], v[18:19], v[162:163] op_sel_hi:[1,0]
	v_pk_add_f32 v[98:99], v[98:99], v[0:1] op_sel_hi:[1,0] neg_lo:[0,1] neg_hi:[0,1]
	v_pk_add_f32 v[52:53], v[52:53], v[0:1] op_sel_hi:[1,0] neg_lo:[0,1] neg_hi:[0,1]
	v_pk_add_f32 v[68:69], v[68:69], v[0:1] op_sel_hi:[1,0] neg_lo:[0,1] neg_hi:[0,1]
	v_pk_add_f32 v[84:85], v[84:85], v[0:1] op_sel_hi:[1,0] neg_lo:[0,1] neg_hi:[0,1]
	v_pk_add_f32 v[100:101], v[100:101], v[0:1] op_sel_hi:[1,0] neg_lo:[0,1] neg_hi:[0,1]
	v_pk_add_f32 v[54:55], v[54:55], v[0:1] op_sel_hi:[1,0] neg_lo:[0,1] neg_hi:[0,1]
	v_pk_add_f32 v[70:71], v[70:71], v[0:1] op_sel_hi:[1,0] neg_lo:[0,1] neg_hi:[0,1]
	v_pk_add_f32 v[86:87], v[86:87], v[0:1] op_sel_hi:[1,0] neg_lo:[0,1] neg_hi:[0,1]
	v_pk_add_f32 v[102:103], v[102:103], v[0:1] op_sel_hi:[1,0] neg_lo:[0,1] neg_hi:[0,1]
	v_pk_add_f32 v[56:57], v[56:57], v[0:1] op_sel_hi:[1,0] neg_lo:[0,1] neg_hi:[0,1]
	v_pk_add_f32 v[72:73], v[72:73], v[0:1] op_sel_hi:[1,0] neg_lo:[0,1] neg_hi:[0,1]
	v_pk_add_f32 v[88:89], v[88:89], v[0:1] op_sel_hi:[1,0] neg_lo:[0,1] neg_hi:[0,1]
	v_pk_add_f32 v[104:105], v[104:105], v[0:1] op_sel_hi:[1,0] neg_lo:[0,1] neg_hi:[0,1]
	v_pk_add_f32 v[58:59], v[58:59], v[0:1] op_sel_hi:[1,0] neg_lo:[0,1] neg_hi:[0,1]
	v_pk_add_f32 v[74:75], v[74:75], v[0:1] op_sel_hi:[1,0] neg_lo:[0,1] neg_hi:[0,1]
	v_pk_add_f32 v[90:91], v[90:91], v[0:1] op_sel_hi:[1,0] neg_lo:[0,1] neg_hi:[0,1]
	v_pk_add_f32 v[106:107], v[106:107], v[0:1] op_sel_hi:[1,0] neg_lo:[0,1] neg_hi:[0,1]
	v_pk_add_f32 v[60:61], v[60:61], v[0:1] op_sel_hi:[1,0] neg_lo:[0,1] neg_hi:[0,1]
	v_pk_add_f32 v[76:77], v[76:77], v[0:1] op_sel_hi:[1,0] neg_lo:[0,1] neg_hi:[0,1]
	v_pk_add_f32 v[92:93], v[92:93], v[0:1] op_sel_hi:[1,0] neg_lo:[0,1] neg_hi:[0,1]
	v_pk_add_f32 v[108:109], v[108:109], v[0:1] op_sel_hi:[1,0] neg_lo:[0,1] neg_hi:[0,1]
	v_pk_add_f32 v[62:63], v[62:63], v[0:1] op_sel_hi:[1,0] neg_lo:[0,1] neg_hi:[0,1]
	v_pk_add_f32 v[78:79], v[78:79], v[0:1] op_sel_hi:[1,0] neg_lo:[0,1] neg_hi:[0,1]
	v_pk_add_f32 v[94:95], v[94:95], v[0:1] op_sel_hi:[1,0] neg_lo:[0,1] neg_hi:[0,1]
	v_pk_add_f32 v[110:111], v[110:111], v[0:1] op_sel_hi:[1,0] neg_lo:[0,1] neg_hi:[0,1]
	v_pk_add_f32 v[64:65], v[64:65], v[0:1] op_sel_hi:[1,0] neg_lo:[0,1] neg_hi:[0,1]
	v_pk_add_f32 v[80:81], v[80:81], v[0:1] op_sel_hi:[1,0] neg_lo:[0,1] neg_hi:[0,1]
	v_pk_add_f32 v[96:97], v[96:97], v[0:1] op_sel_hi:[1,0] neg_lo:[0,1] neg_hi:[0,1]
	v_pk_add_f32 v[112:113], v[112:113], v[0:1] op_sel_hi:[1,0] neg_lo:[0,1] neg_hi:[0,1]
	v_sub_f32_e32 v49, v49, v0
	v_sub_f32_e32 v48, v48, v0
	v_sub_f32_e32 v47, v47, v0
	v_sub_f32_e32 v46, v46, v0
	v_sub_f32_e32 v45, v45, v0
	v_sub_f32_e32 v44, v44, v0
	v_sub_f32_e32 v43, v43, v0
	v_sub_f32_e32 v42, v42, v0
	v_sub_f32_e32 v41, v41, v0
	v_sub_f32_e32 v40, v40, v0
	v_sub_f32_e32 v39, v39, v0
	v_sub_f32_e32 v38, v38, v0
	v_sub_f32_e32 v37, v37, v0
	v_sub_f32_e32 v36, v36, v0
	v_sub_f32_e32 v35, v35, v0
	v_sub_f32_e32 v34, v34, v0

; #define GLOAD(kt_, KR, VR) do { _Pragma("unroll") for (int i = 0; i < KCH; ++i) if (krow_[i] < 64) KR[i] = *(const u32x4*)(kbase + (size_t)((kt_) * 64 + krow_[i]) * HK * DQ + kcol_[i]); \
;     VR = *(const u32x4*)(vbase + (size_t)(kt_) * 4096 + vrow * 64 + vcol); } while (0)
; template <int DQ>
; DI void attn_dense_item(const u16* __restrict__ Q, int qh, const u16* __restrict__ Kp, int HK, int kh, const u16* __restrict__ Vt,
;                         int S, int s0, int qblk, u16* __restrict__ MER, int ocol, float* __restrict__ ssqo, int slot, unsigned char* smem) {
;     ...
;     if (kt + 4 < nkt) { GLOAD(kt + 4, krA, vrA); GLOAD(kt + 5, krB, vrB); }
.Lgqa_B_st_end:
	v_add_f32_e32 v165, v62, v165
	v_add_f32_e32 v242, v63, v64
	v_add_f32_e32 v165, v65, v165
	v_add_f32_e32 v242, v74, v242
	s_waitcnt lgkmcnt(6)
	v_mfma_f32_32x32x16_bf16 v[50:65], v[214:217], v[114:117], v[34:49]
	ds_read_b128 v[214:217], v0 offset:4704
	v_add_f32_e32 v165, v75, v165
	v_add_f32_e32 v242, v76, v242
	v_add_f32_e32 v165, v77, v165
	v_add_f32_e32 v242, v78, v242
	v_add_f32_e32 v165, v79, v165
	v_add_f32_e32 v242, v80, v242
	s_waitcnt lgkmcnt(6)
	v_mfma_f32_32x32x16_bf16 v[50:65], v[218:221], v[118:121], v[50:65]
	ds_read_b128 v[218:221], v0
	v_add_f32_e32 v165, v81, v165
	v_add_f32_e32 v242, v106, v242
	v_add_f32_e32 v165, v107, v165
	v_add_f32_e32 v242, v108, v242
	v_add_f32_e32 v165, v109, v165
	v_add_f32_e32 v242, v110, v242
	s_waitcnt lgkmcnt(6)
	v_mfma_f32_32x32x16_bf16 v[50:65], v[222:225], v[122:125], v[50:65]
	ds_read_b128 v[222:225], v0 offset:32
.Lgqa_B_356:
	s_cmp_ge_u32 s12, s23
	s_cbranch_scc1 .Lgqa_B_ls_end
	s_and_saveexec_b64 s[4:5], s[0:1]
	s_cbranch_execz .Lgqa_B_359
	global_load_dwordx4 v[130:133], v[154:155], off
.Lgqa_B_359:
	s_or_b64 exec, exec, s[4:5]
	global_load_dwordx4 v[138:141], v[156:157], off
	s_mov_b64 vcc, 0x4000
	v_lshl_add_u64 v[244:245], v[154:155], 0, vcc
	s_and_saveexec_b64 s[4:5], s[0:1]
	s_cbranch_execz .Lgqa_B_346
	global_load_dwordx4 v[134:137], v[244:245], off
.Lgqa_B_346:
	s_or_b64 exec, exec, s[4:5]
	s_mov_b64 vcc, 0x2000
	v_lshl_add_u64 v[244:245], v[156:157], 0, vcc
	global_load_dwordx4 v[142:145], v[244:245], off
.Lgqa_B_ls_end:
	v_add_f32_e32 v165, v111, v165
	v_add_f32_e32 v242, v112, v242
	v_add_f32_e32 v165, v113, v165
	v_add_f32_e32 v242, v82, v242
	v_add_f32_e32 v165, v83, v165
	v_add_f32_e32 v242, v84, v242
	s_waitcnt lgkmcnt(6)
	v_mfma_f32_32x32x16_bf16 v[50:65], v[226:229], v[126:129], v[50:65]
	ds_read_b128 v[226:229], v0 offset:64
	v_add_f32_e32 v165, v85, v165
	v_add_f32_e32 v242, v86, v242
	v_add_f32_e32 v165, v87, v165
	v_add_f32_e32 v242, v88, v242
	v_add_f32_e32 v165, v89, v165
	v_add_f32_e32 v242, v90, v242
	s_waitcnt lgkmcnt(6)
	v_mfma_f32_32x32x16_bf16 v[66:81], v[230:233], v[114:117], v[34:49]
	ds_read_b128 v[230:233], v0 offset:96
	v_add_f32_e32 v165, v91, v165
	v_add_f32_e32 v242, v92, v242
	v_add_f32_e32 v165, v93, v165
	v_add_f32_e32 v242, v94, v242
	v_add_f32_e32 v165, v95, v165
	s_waitcnt lgkmcnt(6)
	v_mfma_f32_32x32x16_bf16 v[66:81], v[234:237], v[118:121], v[66:81]
	ds_read_b128 v[234:237], v0 offset:13824
	v_add_f32_e32 v242, v96, v242
	v_add_f32_e32 v165, v97, v165
	v_add_f32_e32 v242, v166, v242
	v_add_f32_e32 v165, v167, v165
	v_add_f32_e32 v242, v168, v242
	s_waitcnt lgkmcnt(6)
	v_mfma_f32_32x32x16_bf16 v[66:81], v[238:241], v[122:125], v[66:81]
	ds_read_b128 v[238:241], v0 offset:13856
	v_add_f32_e32 v165, v169, v165
	v_add_f32_e32 v242, v170, v242
	v_add_f32_e32 v165, v171, v165
	v_add_f32_e32 v242, v172, v242
	v_add_f32_e32 v165, v173, v165
	v_max3_f32 v146, v50, v51, v52
	v_max3_f32 v146, v146, v53, v54
	s_waitcnt lgkmcnt(6)
	v_mfma_f32_32x32x16_bf16 v[66:81], v[214:217], v[126:129], v[66:81]
	ds_read_b128 v[214:217], v0 offset:13888
	v_add_f32_e32 v242, v174, v242
	v_add_f32_e32 v165, v175, v165
	v_add_f32_e32 v242, v176, v242
	v_add_f32_e32 v165, v177, v165
	v_add_f32_e32 v242, v178, v242
	v_max3_f32 v146, v146, v55, v56
	v_max3_f32 v146, v146, v57, v58
	s_waitcnt lgkmcnt(6)
	v_mfma_f32_32x32x16_bf16 v[98:113], v[218:221], v[114:117], v[34:49]
	ds_read_b128 v[218:221], v0 offset:13920
	v_add_f32_e32 v165, v179, v165
	v_add_f32_e32 v242, v191, v242
	v_add_f32_e32 v165, v192, v165
	v_add_f32_e32 v242, v193, v242
	v_max3_f32 v146, v146, v59, v60
	v_max3_f32 v146, v146, v61, v62
	s_waitcnt lgkmcnt(6)
	v_mfma_f32_32x32x16_bf16 v[98:113], v[222:225], v[118:121], v[98:113]
	ds_read_b128 v[206:209], v0 offset:36864
	v_add_f32_e32 v165, v194, v165
	v_add_f32_e32 v242, v195, v242
	v_add_f32_e32 v165, v196, v165
	v_add_f32_e32 v242, v197, v242
	v_max3_f32 v146, v146, v63, v64
	v_max3_f32 v146, v146, v65, v65
	s_waitcnt lgkmcnt(6)
	v_mfma_f32_32x32x16_bf16 v[98:113], v[226:229], v[122:125], v[98:113]
	ds_read_b128 v[210:213], v0 offset:41472
	v_add_f32_e32 v165, v198, v165
	v_add_f32_e32 v242, v199, v242
	v_add_f32_e32 v165, v200, v165
	v_add_f32_e32 v242, v201, v242
	v_max3_f32 v146, v146, v66, v67
	v_max3_f32 v146, v146, v68, v69
	s_waitcnt lgkmcnt(6)
	v_mfma_f32_32x32x16_bf16 v[98:113], v[230:233], v[126:129], v[98:113]
	ds_read_b128 v[222:225], v0 offset:36896
	v_add_f32_e32 v165, v202, v165
	v_add_f32_e32 v242, v203, v242
	v_add_f32_e32 v165, v204, v165
	v_add_f32_e32 v165, v242, v165
	v_max3_f32 v146, v146, v70, v71
	v_max3_f32 v146, v146, v72, v73
	s_waitcnt lgkmcnt(6)
	v_mfma_f32_32x32x16_bf16 v[82:97], v[234:237], v[114:117], v[34:49]
	ds_read_b128 v[226:229], v0 offset:41504
	v_max3_f32 v146, v146, v74, v75
	v_max3_f32 v146, v146, v76, v77
	s_waitcnt lgkmcnt(6)
	v_mfma_f32_32x32x16_bf16 v[82:97], v[238:241], v[118:121], v[82:97]
	ds_read_b128 v[230:233], v0 offset:36928
	v_max3_f32 v146, v146, v78, v79
	v_max3_f32 v146, v146, v80, v81
	s_waitcnt lgkmcnt(6)
	v_mfma_f32_32x32x16_bf16 v[82:97], v[214:217], v[122:125], v[82:97]
	ds_read_b128 v[234:237], v0 offset:41536
	s_waitcnt lgkmcnt(6)
	v_mfma_f32_32x32x16_bf16 v[82:97], v[218:221], v[126:129], v[82:97]
	v_max3_f32 v146, v146, v98, v99
	v_max3_f32 v146, v146, v100, v101
	v_max3_f32 v146, v146, v102, v103
	v_max3_f32 v146, v146, v104, v105
	v_max3_f32 v146, v146, v106, v107
	v_max3_f32 v146, v146, v108, v109
	v_max3_f32 v146, v146, v110, v111
	v_max3_f32 v146, v146, v112, v113
	s_nop 3
	v_max3_f32 v146, v146, v82, v83
	v_max3_f32 v146, v146, v84, v85
	v_max3_f32 v146, v146, v86, v87
	v_max3_f32 v146, v146, v88, v89
	v_max3_f32 v146, v146, v90, v91
	v_max3_f32 v146, v146, v92, v93
	v_max3_f32 v146, v146, v94, v95
	v_max3_f32 v146, v146, v96, v97
	v_mov_b32_e32 v147, v146
	s_nop 1
	v_permlane32_swap_b32_e32 v146, v147
	v_max_f32_e32 v146, v146, v147
	v_cmp_lt_f32_e32 vcc, s50, v146
	s_cbranch_vccz .LBB0_350
	v_max_f32_e32 v146, v146, v146
	v_max_f32_e32 v146, 0, v146
	v_exp_f32_e64 v148, -v146
	v_pk_add_f32 v[98:99], v[98:99], v[146:147] op_sel_hi:[1,0] neg_lo:[0,1] neg_hi:[0,1]
	v_pk_add_f32 v[66:67], v[66:67], v[146:147] op_sel_hi:[1,0] neg_lo:[0,1] neg_hi:[0,1]
	v_pk_add_f32 v[50:51], v[50:51], v[146:147] op_sel_hi:[1,0] neg_lo:[0,1] neg_hi:[0,1]
	v_mul_f32_e32 v165, v165, v148
	v_pk_mul_f32 v[16:17], v[16:17], v[148:149] op_sel_hi:[1,0]
	v_pk_mul_f32 v[14:15], v[14:15], v[148:149] op_sel_hi:[1,0]
	v_pk_mul_f32 v[12:13], v[12:13], v[148:149] op_sel_hi:[1,0]
	v_pk_mul_f32 v[10:11], v[10:11], v[148:149] op_sel_hi:[1,0]
	v_pk_mul_f32 v[8:9], v[8:9], v[148:149] op_sel_hi:[1,0]
	v_pk_mul_f32 v[6:7], v[6:7], v[148:149] op_sel_hi:[1,0]
	v_pk_mul_f32 v[4:5], v[4:5], v[148:149] op_sel_hi:[1,0]
	v_pk_mul_f32 v[2:3], v[2:3], v[148:149] op_sel_hi:[1,0]
	v_pk_mul_f32 v[32:33], v[32:33], v[148:149] op_sel_hi:[1,0]
	v_pk_mul_f32 v[30:31], v[30:31], v[148:149] op_sel_hi:[1,0]
	v_pk_mul_f32 v[28:29], v[28:29], v[148:149] op_sel_hi:[1,0]
	v_pk_mul_f32 v[26:27], v[26:27], v[148:149] op_sel_hi:[1,0]
	v_pk_mul_f32 v[24:25], v[24:25], v[148:149] op_sel_hi:[1,0]
	v_pk_mul_f32 v[22:23], v[22:23], v[148:149] op_sel_hi:[1,0]
	v_pk_mul_f32 v[20:21], v[20:21], v[148:149] op_sel_hi:[1,0]
	v_pk_mul_f32 v[18:19], v[18:19], v[148:149] op_sel_hi:[1,0]
	v_pk_add_f32 v[82:83], v[82:83], v[146:147] op_sel_hi:[1,0] neg_lo:[0,1] neg_hi:[0,1]
	v_pk_add_f32 v[100:101], v[100:101], v[146:147] op_sel_hi:[1,0] neg_lo:[0,1] neg_hi:[0,1]
	v_pk_add_f32 v[68:69], v[68:69], v[146:147] op_sel_hi:[1,0] neg_lo:[0,1] neg_hi:[0,1]
	v_pk_add_f32 v[52:53], v[52:53], v[146:147] op_sel_hi:[1,0] neg_lo:[0,1] neg_hi:[0,1]
	v_pk_add_f32 v[84:85], v[84:85], v[146:147] op_sel_hi:[1,0] neg_lo:[0,1] neg_hi:[0,1]
	v_pk_add_f32 v[102:103], v[102:103], v[146:147] op_sel_hi:[1,0] neg_lo:[0,1] neg_hi:[0,1]
	v_pk_add_f32 v[70:71], v[70:71], v[146:147] op_sel_hi:[1,0] neg_lo:[0,1] neg_hi:[0,1]
	v_pk_add_f32 v[54:55], v[54:55], v[146:147] op_sel_hi:[1,0] neg_lo:[0,1] neg_hi:[0,1]
	v_pk_add_f32 v[86:87], v[86:87], v[146:147] op_sel_hi:[1,0] neg_lo:[0,1] neg_hi:[0,1]
	v_pk_add_f32 v[104:105], v[104:105], v[146:147] op_sel_hi:[1,0] neg_lo:[0,1] neg_hi:[0,1]
	v_pk_add_f32 v[72:73], v[72:73], v[146:147] op_sel_hi:[1,0] neg_lo:[0,1] neg_hi:[0,1]
	v_pk_add_f32 v[56:57], v[56:57], v[146:147] op_sel_hi:[1,0] neg_lo:[0,1] neg_hi:[0,1]
	v_pk_add_f32 v[88:89], v[88:89], v[146:147] op_sel_hi:[1,0] neg_lo:[0,1] neg_hi:[0,1]
	v_pk_add_f32 v[106:107], v[106:107], v[146:147] op_sel_hi:[1,0] neg_lo:[0,1] neg_hi:[0,1]
	v_pk_add_f32 v[74:75], v[74:75], v[146:147] op_sel_hi:[1,0] neg_lo:[0,1] neg_hi:[0,1]
	v_pk_add_f32 v[58:59], v[58:59], v[146:147] op_sel_hi:[1,0] neg_lo:[0,1] neg_hi:[0,1]
	v_pk_add_f32 v[90:91], v[90:91], v[146:147] op_sel_hi:[1,0] neg_lo:[0,1] neg_hi:[0,1]
	v_pk_add_f32 v[108:109], v[108:109], v[146:147] op_sel_hi:[1,0] neg_lo:[0,1] neg_hi:[0,1]
	v_pk_add_f32 v[76:77], v[76:77], v[146:147] op_sel_hi:[1,0] neg_lo:[0,1] neg_hi:[0,1]
	v_pk_add_f32 v[60:61], v[60:61], v[146:147] op_sel_hi:[1,0] neg_lo:[0,1] neg_hi:[0,1]
	v_pk_add_f32 v[92:93], v[92:93], v[146:147] op_sel_hi:[1,0] neg_lo:[0,1] neg_hi:[0,1]
	v_pk_add_f32 v[110:111], v[110:111], v[146:147] op_sel_hi:[1,0] neg_lo:[0,1] neg_hi:[0,1]
	v_pk_add_f32 v[78:79], v[78:79], v[146:147] op_sel_hi:[1,0] neg_lo:[0,1] neg_hi:[0,1]
	v_pk_add_f32 v[62:63], v[62:63], v[146:147] op_sel_hi:[1,0] neg_lo:[0,1] neg_hi:[0,1]
	v_pk_add_f32 v[94:95], v[94:95], v[146:147] op_sel_hi:[1,0] neg_lo:[0,1] neg_hi:[0,1]
	v_pk_add_f32 v[112:113], v[112:113], v[146:147] op_sel_hi:[1,0] neg_lo:[0,1] neg_hi:[0,1]
	v_pk_add_f32 v[80:81], v[80:81], v[146:147] op_sel_hi:[1,0] neg_lo:[0,1] neg_hi:[0,1]
	v_pk_add_f32 v[64:65], v[64:65], v[146:147] op_sel_hi:[1,0] neg_lo:[0,1] neg_hi:[0,1]
	v_pk_add_f32 v[96:97], v[96:97], v[146:147] op_sel_hi:[1,0] neg_lo:[0,1] neg_hi:[0,1]
	v_sub_f32_e32 v49, v49, v146
	v_sub_f32_e32 v48, v48, v146
	v_sub_f32_e32 v47, v47, v146
	v_sub_f32_e32 v46, v46, v146
	v_sub_f32_e32 v45, v45, v146
	v_sub_f32_e32 v44, v44, v146
	v_sub_f32_e32 v43, v43, v146
	v_sub_f32_e32 v42, v42, v146
	v_sub_f32_e32 v41, v41, v146
	v_sub_f32_e32 v40, v40, v146
	v_sub_f32_e32 v39, v39, v146
	v_sub_f32_e32 v38, v38, v146
	v_sub_f32_e32 v37, v37, v146
	v_sub_f32_e32 v36, v36, v146
	v_sub_f32_e32 v35, v35, v146
	v_sub_f32_e32 v34, v34, v146

; __global__ void __launch_bounds__(512, 2) fwd_mega(Params p) {
;   extern __shared__ __attribute__((aligned(16))) unsigned char smem[];
	.amdhsa_kernel _Z8fwd_mega6Params
		.amdhsa_group_segment_fixed_size 0
		.amdhsa_private_segment_fixed_size 0
		.amdhsa_kernarg_size 440
		.amdhsa_user_sgpr_count 2
		.amdhsa_user_sgpr_dispatch_ptr 0
		.amdhsa_user_sgpr_queue_ptr 0
		.amdhsa_user_sgpr_kernarg_segment_ptr 1
		.amdhsa_user_sgpr_dispatch_id 0
		.amdhsa_user_sgpr_kernarg_preload_length 0
		.amdhsa_user_sgpr_kernarg_preload_offset 0
		.amdhsa_user_sgpr_private_segment_size 0
		.amdhsa_uses_dynamic_stack 0
		.amdhsa_enable_private_segment 0
		.amdhsa_system_sgpr_workgroup_id_x 1
		.amdhsa_system_sgpr_workgroup_id_y 0
		.amdhsa_system_sgpr_workgroup_id_z 0
		.amdhsa_system_sgpr_workgroup_info 0
		.amdhsa_system_vgpr_workitem_id 2
		.amdhsa_next_free_vgpr 256
		.amdhsa_next_free_sgpr 100
		.amdhsa_accum_offset 256
		.amdhsa_reserve_vcc 1
		.amdhsa_float_round_mode_32 0
		.amdhsa_float_round_mode_16_64 0
		.amdhsa_float_denorm_mode_32 3
		.amdhsa_float_denorm_mode_16_64 3
		.amdhsa_dx10_clamp 1
		.amdhsa_ieee_mode 1
		.amdhsa_fp16_overflow 0
		.amdhsa_tg_split 0
		.amdhsa_exception_fp_ieee_invalid_op 0
		.amdhsa_exception_fp_denorm_src 0
		.amdhsa_exception_fp_ieee_div_zero 0
		.amdhsa_exception_fp_ieee_overflow 0
		.amdhsa_exception_fp_ieee_underflow 0
		.amdhsa_exception_fp_ieee_inexact 0
		.amdhsa_exception_int_div_zero 0
	.end_amdhsa_kernel

; __global__ void __launch_bounds__(512, 2) fwd_mega(Params p) {
amdhsa.kernels:
  - .agpr_count:     0
    .args:
      - .offset:         0
        .size:           184
        .value_kind:     by_value
      - .offset:         184
        .size:           4
        .value_kind:     hidden_block_count_x
      - .offset:         188
        .size:           4
        .value_kind:     hidden_block_count_y
      - .offset:         192
        .size:           4
        .value_kind:     hidden_block_count_z
      - .offset:         196
        .size:           2
        .value_kind:     hidden_group_size_x
      - .offset:         198
        .size:           2
        .value_kind:     hidden_group_size_y
      - .offset:         200
        .size:           2
        .value_kind:     hidden_group_size_z
      - .offset:         202
        .size:           2
        .value_kind:     hidden_remainder_x
      - .offset:         204
        .size:           2
        .value_kind:     hidden_remainder_y
      - .offset:         206
        .size:           2
        .value_kind:     hidden_remainder_z
      - .offset:         224
        .size:           8
        .value_kind:     hidden_global_offset_x
      - .offset:         232
        .size:           8
        .value_kind:     hidden_global_offset_y
      - .offset:         240
        .size:           8
        .value_kind:     hidden_global_offset_z
      - .offset:         248
        .size:           2
        .value_kind:     hidden_grid_dims
      - .offset:         272
        .size:           8
        .value_kind:     hidden_multigrid_sync_arg
      - .offset:         304
        .size:           4
        .value_kind:     hidden_dynamic_lds_size
    .group_segment_fixed_size: 0
    .kernarg_segment_align: 8
    .kernarg_segment_size: 440
    .language:       OpenCL C
    .language_version:
      - 2
      - 0
    .max_flat_workgroup_size: 512
    .name:           _Z8fwd_mega6Params
    .private_segment_fixed_size: 0
    .sgpr_count:     106
    .sgpr_spill_count: 199
    .symbol:         _Z8fwd_mega6Params.kd
    .uniform_work_group_size: 1
    .uses_dynamic_stack: false
    .vgpr_count:     256
    .vgpr_spill_count: 0
    .wavefront_size: 64
